# v22 + nt hint on the phase-1 epilogue f32 dwordx4 stores (new window / mem_kv rows, written once)
# speedup vs baseline: 1.0008x; 1.0008x over previous
.LBB0_217:
	s_or_b64 exec, exec, s[0:1]
	v_readlane_b32 s0, v255, 34
	v_readlane_b32 s1, v255, 35
	s_add_u32 s0, s0, 0x4940000
	v_readlane_b32 s6, v255, 32
	s_addc_u32 s1, s1, 0
	s_lshl_b32 s5, s6, 2
	v_bfe_u32 v88, v230, 8, 2
	s_and_b32 s6, s5, 4
	v_or_b32_e32 v80, s6, v88
	v_lshlrev_b32_e32 v81, 6, v196
	v_lshl_add_u64 v[68:69], s[60:61], 0, v[222:223]
	v_and_b32_e32 v82, 0x1bc0, v81
	v_lshlrev_b32_e32 v80, 15, v80
	v_mov_b32_e32 v81, v197
	v_lshlrev_b32_e32 v70, 8, v88
	v_mov_b32_e32 v71, v197
	v_lshl_add_u64 v[80:81], v[68:69], 0, v[80:81]
	v_lshlrev_b32_e32 v132, 1, v82
	v_mov_b32_e32 v133, v197
	v_lshl_add_u64 v[70:71], s[0:1], 0, v[70:71]
	v_lshl_add_u64 v[80:81], v[80:81], 0, v[132:133]
	v_lshlrev_b64 v[82:83], 1, v[198:199]
	v_lshlrev_b32_e32 v139, 11, v196
	v_lshl_add_u64 v[70:71], v[198:199], 2, v[70:71]
	v_lshl_add_u64 v[80:81], v[80:81], 0, v[82:83]
	v_or_b32_e32 v196, v209, v139
	v_cvt_pk_bf16_f32 v86, v76, v77
	v_cvt_pk_bf16_f32 v87, v78, v79
	v_lshl_add_u64 v[84:85], v[70:71], 0, v[196:197]
	s_waitcnt vmcnt(0)
	flat_store_dwordx2 v[80:81], v[86:87]
	flat_store_dwordx4 v[84:85], v[76:79] nt
	v_readlane_b32 s7, v255, 33
	s_and_b32 s7, s5, 12
	v_cvt_pk_bf16_f32 v76, v72, v73
	v_cvt_pk_bf16_f32 v77, v74, v75
	flat_store_dwordx2 v[80:81], v[76:77] offset:32
	flat_store_dwordx4 v[84:85], v[72:75] offset:64 nt
	v_lshlrev_b32_e32 v144, 11, v212
	v_mov_b32_e32 v135, v197
	v_cvt_pk_bf16_f32 v72, v64, v65
	v_cvt_pk_bf16_f32 v73, v66, v67
	flat_store_dwordx2 v[80:81], v[72:73] offset:64
	flat_store_dwordx4 v[84:85], v[64:67] offset:128 nt
	v_cvt_pk_bf16_f32 v72, v108, v109
	v_cvt_pk_bf16_f32 v73, v110, v111
	v_cvt_pk_bf16_f32 v64, v148, v149
	v_cvt_pk_bf16_f32 v65, v150, v151
	flat_store_dwordx2 v[80:81], v[64:65] offset:96
	flat_store_dwordx4 v[84:85], v[148:151] offset:192 nt
	v_or_b32_e32 v64, s7, v88
	v_lshlrev_b32_e32 v65, 6, v212
	v_and_b32_e32 v66, 0x3fc0, v65
	v_lshlrev_b32_e32 v196, 15, v64
	v_lshl_add_u64 v[64:65], v[68:69], 0, v[196:197]
	v_lshlrev_b32_e32 v196, 1, v66
	v_lshl_add_u64 v[66:67], v[64:65], 0, v[196:197]
	v_lshl_add_u64 v[66:67], v[66:67], 0, v[82:83]
	v_or_b32_e32 v68, v209, v144
	v_mov_b32_e32 v69, v197
	v_lshl_add_u64 v[68:69], v[70:71], 0, v[68:69]
	flat_store_dwordx2 v[66:67], v[72:73]
	flat_store_dwordx4 v[68:69], v[108:111] nt
	v_cvt_pk_bf16_f32 v72, v100, v101
	v_cvt_pk_bf16_f32 v73, v102, v103
	flat_store_dwordx2 v[66:67], v[72:73] offset:32
	flat_store_dwordx4 v[68:69], v[100:103] offset:64 nt
	v_cvt_pk_bf16_f32 v72, v96, v97
	v_cvt_pk_bf16_f32 v73, v98, v99
	flat_store_dwordx2 v[66:67], v[72:73] offset:64
	flat_store_dwordx4 v[68:69], v[96:99] offset:128 nt
	v_cvt_pk_bf16_f32 v72, v152, v153
	v_cvt_pk_bf16_f32 v73, v154, v155
	flat_store_dwordx2 v[66:67], v[72:73] offset:96
	flat_store_dwordx4 v[68:69], v[152:155] offset:192 nt
	v_lshlrev_b32_e32 v66, 6, v210
	v_and_b32_e32 v66, 0x3bc0, v66
	v_lshlrev_b32_e32 v134, 1, v66
	v_lshl_add_u64 v[66:67], v[64:65], 0, v[134:135]
	v_lshlrev_b32_e32 v145, 11, v210
	v_lshl_add_u64 v[66:67], v[66:67], 0, v[82:83]
	v_or_b32_e32 v68, v209, v145
	v_mov_b32_e32 v69, v197
	v_cvt_pk_bf16_f32 v72, v120, v121
	v_cvt_pk_bf16_f32 v73, v122, v123
	v_lshl_add_u64 v[68:69], v[70:71], 0, v[68:69]
	flat_store_dwordx2 v[66:67], v[72:73]
	flat_store_dwordx4 v[68:69], v[120:123] nt
	v_cvt_pk_bf16_f32 v72, v116, v117
	v_cvt_pk_bf16_f32 v73, v118, v119
	flat_store_dwordx2 v[66:67], v[72:73] offset:32
	flat_store_dwordx4 v[68:69], v[116:119] offset:64 nt
	v_cvt_pk_bf16_f32 v72, v112, v113
	v_cvt_pk_bf16_f32 v73, v114, v115
	flat_store_dwordx2 v[66:67], v[72:73] offset:64
	flat_store_dwordx4 v[68:69], v[112:115] offset:128 nt
	v_cvt_pk_bf16_f32 v72, v164, v165
	v_cvt_pk_bf16_f32 v73, v166, v167
	flat_store_dwordx2 v[66:67], v[72:73] offset:96
	flat_store_dwordx4 v[68:69], v[164:167] offset:192 nt
	v_lshlrev_b32_e32 v66, 6, v208
	v_and_b32_e32 v66, 0x3fc0, v66
	v_lshlrev_b32_e32 v136, 1, v66
	v_mov_b32_e32 v137, v197
	v_lshl_add_u64 v[64:65], v[64:65], 0, v[136:137]
	v_lshlrev_b32_e32 v146, 11, v208
	v_lshl_add_u64 v[64:65], v[64:65], 0, v[82:83]
	v_or_b32_e32 v66, v209, v146
	v_mov_b32_e32 v67, v197
	v_cvt_pk_bf16_f32 v68, v124, v125
	v_cvt_pk_bf16_f32 v69, v126, v127
	v_lshl_add_u64 v[66:67], v[70:71], 0, v[66:67]
	flat_store_dwordx2 v[64:65], v[68:69]
	flat_store_dwordx4 v[66:67], v[124:127] nt
	v_cvt_pk_bf16_f32 v68, v128, v129
	v_cvt_pk_bf16_f32 v69, v130, v131
	flat_store_dwordx2 v[64:65], v[68:69] offset:32
	flat_store_dwordx4 v[66:67], v[128:131] offset:64 nt
	v_cvt_pk_bf16_f32 v68, v140, v141
	v_cvt_pk_bf16_f32 v69, v142, v143
	flat_store_dwordx2 v[64:65], v[68:69] offset:64
	flat_store_dwordx4 v[66:67], v[140:143] offset:128 nt
	v_cvt_pk_bf16_f32 v68, v176, v177
	v_cvt_pk_bf16_f32 v69, v178, v179
	flat_store_dwordx2 v[64:65], v[68:69] offset:96
	flat_store_dwordx4 v[66:67], v[176:179] offset:192 nt
	flat_load_dword v140, v[200:201]
	flat_load_dword v138, v[202:203]
	flat_load_dword v130, v[204:205]
	flat_load_dword v128, v[206:207]
	v_add3_u32 v129, v231, s4, 2
	v_cmp_gt_i32_e32 vcc, 4, v129
	s_and_saveexec_b64 s[4:5], vcc
	s_xor_b64 s[4:5], exec, s[4:5]
	s_cbranch_execz .LBB0_219
	v_readlane_b32 s8, v255, 0
	v_lshlrev_b32_e32 v94, 2, v198
	v_readlane_b32 s12, v255, 4
	v_readlane_b32 s13, v255, 5
	s_waitcnt vmcnt(0) lgkmcnt(0)
	v_pk_mul_f32 v[108:109], v[62:63], v[140:141] op_sel_hi:[1,0]
	v_pk_mul_f32 v[116:117], v[54:55], v[138:139] op_sel_hi:[1,0]
	v_pk_mul_f32 v[120:121], v[46:47], v[130:131] op_sel_hi:[1,0]
	v_pk_mul_f32 v[62:63], v[30:31], v[128:129] op_sel_hi:[1,0]
	v_pk_mul_f32 v[118:119], v[60:61], v[140:141] op_sel_hi:[1,0]
	v_pk_mul_f32 v[122:123], v[52:53], v[138:139] op_sel_hi:[1,0]
	v_pk_mul_f32 v[124:125], v[44:45], v[130:131] op_sel_hi:[1,0]
	v_pk_mul_f32 v[60:61], v[28:29], v[128:129] op_sel_hi:[1,0]
	global_load_dwordx4 v[28:31], v94, s[12:13] offset:192
	global_load_dwordx4 v[44:47], v94, s[12:13] offset:128
	v_pk_mul_f32 v[72:73], v[56:57], v[140:141] op_sel_hi:[1,0]
	v_pk_mul_f32 v[56:57], v[36:37], v[138:139] op_sel_hi:[1,0]
	v_pk_mul_f32 v[88:89], v[58:59], v[140:141] op_sel_hi:[1,0]
	v_pk_mul_f32 v[58:59], v[38:39], v[138:139] op_sel_hi:[1,0]
	global_load_dwordx4 v[36:39], v94, s[12:13]
	global_load_dwordx4 v[52:55], v94, s[12:13] offset:64
	v_pk_mul_f32 v[40:41], v[40:41], v[140:141] op_sel_hi:[1,0]
	v_pk_mul_f32 v[24:25], v[24:25], v[138:139] op_sel_hi:[1,0]
	v_mov_b32_e32 v105, v41
	v_mov_b32_e32 v104, v25
	v_pk_mul_f32 v[42:43], v[42:43], v[140:141] op_sel_hi:[1,0]
	v_pk_mul_f32 v[26:27], v[26:27], v[138:139] op_sel_hi:[1,0]
	v_mov_b32_e32 v102, v24
	v_mov_b32_e32 v103, v40
	v_pk_mul_f32 v[104:105], v[104:105], v[104:105]
	v_pk_mul_f32 v[48:49], v[48:49], v[140:141] op_sel_hi:[1,0]
	v_pk_fma_f32 v[102:103], v[102:103], v[102:103], v[104:105]
	v_mov_b32_e32 v104, v26
	v_mov_b32_e32 v105, v42
	v_pk_mul_f32 v[32:33], v[32:33], v[138:139] op_sel_hi:[1,0]
	v_mov_b32_e32 v106, v27
	v_mov_b32_e32 v107, v43
	v_pk_fma_f32 v[102:103], v[104:105], v[104:105], v[102:103]
	v_mov_b32_e32 v94, v32
	v_mov_b32_e32 v95, v48
	v_pk_fma_f32 v[102:103], v[106:107], v[106:107], v[102:103]
	v_pk_mul_f32 v[50:51], v[50:51], v[140:141] op_sel_hi:[1,0]
	v_pk_mul_f32 v[34:35], v[34:35], v[138:139] op_sel_hi:[1,0]
	v_mov_b32_e32 v96, v33
	v_mov_b32_e32 v97, v49
	v_pk_fma_f32 v[94:95], v[94:95], v[94:95], v[102:103]
	v_and_b32_e32 v65, 64, v195
	v_mov_b32_e32 v98, v34
	v_mov_b32_e32 v99, v50
	v_pk_fma_f32 v[94:95], v[96:97], v[96:97], v[94:95]
	v_xor_b32_e32 v64, 16, v195
	v_add_u32_e32 v65, 64, v65
	v_pk_mul_f32 v[74:75], v[72:73], v[72:73]
	v_pk_mul_f32 v[86:87], v[56:57], v[56:57]
	v_mov_b32_e32 v100, v35
	v_mov_b32_e32 v101, v51
	v_pk_fma_f32 v[94:95], v[98:99], v[98:99], v[94:95]
	v_cmp_lt_i32_e32 vcc, v64, v65
	v_pk_fma_f32 v[94:95], v[100:101], v[100:101], v[94:95]
	v_mov_b32_e32 v96, v86
	v_mov_b32_e32 v97, v74
	v_cndmask_b32_e32 v64, v195, v64, vcc
	v_pk_mul_f32 v[90:91], v[88:89], v[88:89]
	v_pk_mul_f32 v[92:93], v[58:59], v[58:59]
	v_pk_add_f32 v[94:95], v[96:97], v[94:95]
	v_mov_b32_e32 v74, v87
	v_lshlrev_b32_e32 v111, 2, v64
	v_xor_b32_e32 v64, 32, v195
	v_pk_add_f32 v[74:75], v[74:75], v[94:95]
	v_mov_b32_e32 v86, v92
	v_mov_b32_e32 v87, v90
	v_cmp_lt_i32_e32 vcc, v64, v65
	v_pk_mul_f32 v[68:69], v[118:119], v[118:119]
	v_pk_mul_f32 v[70:71], v[122:123], v[122:123]
	v_pk_add_f32 v[74:75], v[86:87], v[74:75]
	v_mov_b32_e32 v90, v93
	v_cndmask_b32_e32 v64, v195, v64, vcc
	v_pk_add_f32 v[74:75], v[90:91], v[74:75]
	v_mov_b32_e32 v86, v70
	v_mov_b32_e32 v87, v68
	v_lshlrev_b32_e32 v112, 2, v64
	v_pk_mul_f32 v[64:65], v[108:109], v[108:109]
	v_pk_mul_f32 v[66:67], v[116:117], v[116:117]
	v_pk_add_f32 v[74:75], v[86:87], v[74:75]
	v_mov_b32_e32 v68, v71
	v_pk_add_f32 v[68:69], v[68:69], v[74:75]
	v_mov_b32_e32 v70, v66
	v_mov_b32_e32 v71, v64
	v_pk_add_f32 v[68:69], v[70:71], v[68:69]
	v_mov_b32_e32 v64, v67
	v_pk_add_f32 v[64:65], v[64:65], v[68:69]
	ds_bpermute_b32 v67, v111, v65
	ds_bpermute_b32 v66, v111, v64
	v_readlane_b32 s9, v255, 1
	s_mov_b32 s8, 0x358637bd
	v_pk_mul_f32 v[4:5], v[4:5], v[130:131] op_sel_hi:[1,0]
	v_mov_b64_e32 v[94:95], s[8:9]
	s_waitcnt lgkmcnt(0)
	v_pk_add_f32 v[64:65], v[64:65], v[66:67]
	ds_bpermute_b32 v67, v112, v65
	ds_bpermute_b32 v66, v112, v64
	s_mov_b32 s8, 0x3c800000
	v_pk_mul_f32 v[0:1], v[0:1], v[128:129] op_sel_hi:[1,0]
	v_mov_b32_e32 v101, v5
	v_mov_b32_e32 v100, v1
	s_waitcnt lgkmcnt(0)
	v_pk_add_f32 v[64:65], v[64:65], v[66:67]
	v_pk_mul_f32 v[6:7], v[6:7], v[130:131] op_sel_hi:[1,0]
	v_pk_fma_f32 v[74:75], v[64:65], s[8:9], v[94:95] op_sel_hi:[1,0,0]
	v_pk_mul_f32 v[2:3], v[2:3], v[128:129] op_sel_hi:[1,0]
	v_mul_f32_e32 v64, 0x4b800000, v75
	v_cmp_gt_f32_e32 vcc, s63, v75
	v_mov_b32_e32 v98, v0
	v_mov_b32_e32 v99, v4
	v_cndmask_b32_e32 v64, v75, v64, vcc
	v_rsq_f32_e32 v64, v64
	v_pk_mul_f32 v[100:101], v[100:101], v[100:101]
	v_pk_mul_f32 v[16:17], v[16:17], v[130:131] op_sel_hi:[1,0]
	v_pk_fma_f32 v[98:99], v[98:99], v[98:99], v[100:101]
	v_mul_f32_e32 v65, 0x45800000, v64
	v_cndmask_b32_e32 v110, v64, v65, vcc
	s_waitcnt vmcnt(0)
	v_pk_mul_f32 v[70:71], v[54:55], v[110:111] op_sel_hi:[1,0]
	v_cmp_gt_f32_e32 vcc, s63, v74
	v_pk_mul_f32 v[70:71], v[50:51], v[70:71]
	v_mul_f32_e32 v50, 0x4b800000, v74
	v_pk_mul_f32 v[66:67], v[46:47], v[110:111] op_sel_hi:[1,0]
	v_cndmask_b32_e32 v50, v74, v50, vcc
	v_pk_mul_f32 v[66:67], v[88:89], v[66:67]
	v_rsq_f32_e32 v88, v50
	v_pk_mul_f32 v[68:69], v[52:53], v[110:111] op_sel_hi:[1,0]
	v_mov_b32_e32 v100, v2
	v_mov_b32_e32 v101, v6
	v_pk_mul_f32 v[8:9], v[8:9], v[128:129] op_sel_hi:[1,0]
	v_pk_mul_f32 v[64:65], v[44:45], v[110:111] op_sel_hi:[1,0]
	v_pk_mul_f32 v[68:69], v[48:49], v[68:69]
	v_pk_mul_f32 v[48:49], v[36:37], v[110:111] op_sel_hi:[1,0]
	v_mov_b32_e32 v102, v3
	v_mov_b32_e32 v103, v7
	v_pk_fma_f32 v[98:99], v[100:101], v[100:101], v[98:99]
	v_pk_mul_f32 v[64:65], v[72:73], v[64:65]
	v_pk_mul_f32 v[50:51], v[38:39], v[110:111] op_sel_hi:[1,0]
	v_pk_mul_f32 v[72:73], v[40:41], v[48:49]
	v_mov_b32_e32 v48, v8
	v_mov_b32_e32 v49, v16
	v_pk_fma_f32 v[98:99], v[102:103], v[102:103], v[98:99]
	v_pk_mul_f32 v[18:19], v[18:19], v[130:131] op_sel_hi:[1,0]
	v_pk_mul_f32 v[10:11], v[10:11], v[128:129] op_sel_hi:[1,0]
	v_pk_mul_f32 v[74:75], v[42:43], v[50:51]
	v_mul_f32_e32 v40, 0x45800000, v88
	v_mov_b32_e32 v50, v9
	v_mov_b32_e32 v51, v17
	v_pk_fma_f32 v[48:49], v[48:49], v[48:49], v[98:99]
	v_pk_mul_f32 v[20:21], v[20:21], v[130:131] op_sel_hi:[1,0]
	v_pk_mul_f32 v[12:13], v[12:13], v[128:129] op_sel_hi:[1,0]
	v_cndmask_b32_e32 v40, v88, v40, vcc
	v_mov_b32_e32 v88, v10
	v_mov_b32_e32 v89, v18
	v_pk_fma_f32 v[48:49], v[50:51], v[50:51], v[48:49]
	v_pk_mul_f32 v[84:85], v[20:21], v[20:21]
	v_pk_mul_f32 v[86:87], v[12:13], v[12:13]
	v_mov_b32_e32 v96, v11
	v_mov_b32_e32 v97, v19
	v_pk_fma_f32 v[48:49], v[88:89], v[88:89], v[48:49]
	v_pk_mul_f32 v[22:23], v[22:23], v[130:131] op_sel_hi:[1,0]
	v_pk_mul_f32 v[14:15], v[14:15], v[128:129] op_sel_hi:[1,0]
	v_pk_fma_f32 v[48:49], v[96:97], v[96:97], v[48:49]
	v_mov_b32_e32 v50, v86
	v_mov_b32_e32 v51, v84
	v_pk_mul_f32 v[90:91], v[22:23], v[22:23]
	v_pk_mul_f32 v[92:93], v[14:15], v[14:15]
	v_pk_add_f32 v[48:49], v[50:51], v[48:49]
	v_mov_b32_e32 v84, v87
	v_pk_add_f32 v[48:49], v[84:85], v[48:49]
	v_mov_b32_e32 v50, v92
	v_mov_b32_e32 v51, v90
	v_pk_mul_f32 v[80:81], v[124:125], v[124:125]
	v_pk_mul_f32 v[82:83], v[60:61], v[60:61]
	v_pk_add_f32 v[48:49], v[50:51], v[48:49]
	v_mov_b32_e32 v90, v93
	v_pk_add_f32 v[48:49], v[90:91], v[48:49]
	v_mov_b32_e32 v50, v82
	v_mov_b32_e32 v51, v80
	v_pk_mul_f32 v[76:77], v[120:121], v[120:121]
	v_pk_mul_f32 v[78:79], v[62:63], v[62:63]
	v_pk_add_f32 v[48:49], v[50:51], v[48:49]
	v_mov_b32_e32 v80, v83
	v_pk_add_f32 v[48:49], v[80:81], v[48:49]
	v_mov_b32_e32 v50, v78
	v_mov_b32_e32 v51, v76
	v_pk_add_f32 v[48:49], v[50:51], v[48:49]
	v_mov_b32_e32 v76, v79
	v_pk_add_f32 v[48:49], v[76:77], v[48:49]
	ds_bpermute_b32 v51, v111, v49
	ds_bpermute_b32 v50, v111, v48
	v_pk_mul_f32 v[42:43], v[44:45], v[40:41] op_sel_hi:[1,0]
	v_pk_mul_f32 v[76:77], v[46:47], v[40:41] op_sel_hi:[1,0]
	v_mov_b32_e32 v199, v197
	v_pk_mul_f32 v[78:79], v[58:59], v[76:77]
	s_waitcnt lgkmcnt(0)
	v_pk_add_f32 v[48:49], v[48:49], v[50:51]
	ds_bpermute_b32 v51, v112, v49
	ds_bpermute_b32 v50, v112, v48
	v_pk_mul_f32 v[76:77], v[56:57], v[42:43]
	v_pk_mul_f32 v[56:57], v[54:55], v[40:41] op_sel_hi:[1,0]
	v_pk_mul_f32 v[42:43], v[52:53], v[40:41] op_sel_hi:[1,0]
	v_pk_mul_f32 v[82:83], v[34:35], v[56:57]
	s_waitcnt lgkmcnt(0)
	v_pk_add_f32 v[34:35], v[48:49], v[50:51]
	v_pk_mul_f32 v[80:81], v[32:33], v[42:43]
	v_pk_fma_f32 v[34:35], v[34:35], s[8:9], v[94:95] op_sel_hi:[1,0,0]
	v_pk_mul_f32 v[32:33], v[36:37], v[40:41] op_sel_hi:[1,0]
	v_mul_f32_e32 v41, 0x4b800000, v35
	v_cmp_gt_f32_e32 vcc, s63, v35
	v_pk_mul_f32 v[84:85], v[24:25], v[32:33]
	v_pk_mul_f32 v[42:43], v[38:39], v[40:41] op_sel_hi:[1,0]
	v_cndmask_b32_e32 v35, v35, v41, vcc
	v_rsq_f32_e32 v35, v35
	v_pk_mul_f32 v[86:87], v[26:27], v[42:43]
	v_readlane_b32 s10, v255, 2
	v_readlane_b32 s11, v255, 3
	v_mul_f32_e32 v24, 0x45800000, v35
	v_cndmask_b32_e32 v24, v35, v24, vcc
	v_pk_mul_f32 v[32:33], v[46:47], v[24:25] op_sel_hi:[1,0]
	v_pk_mul_f32 v[26:27], v[44:45], v[24:25] op_sel_hi:[1,0]
	v_pk_mul_f32 v[90:91], v[22:23], v[32:33]
	v_pk_mul_f32 v[22:23], v[54:55], v[24:25] op_sel_hi:[1,0]
	v_cmp_gt_f32_e32 vcc, s63, v34
	v_pk_mul_f32 v[94:95], v[18:19], v[22:23]
	v_mul_f32_e32 v18, 0x4b800000, v34
	v_pk_mul_f32 v[88:89], v[20:21], v[26:27]
	v_pk_mul_f32 v[20:21], v[52:53], v[24:25] op_sel_hi:[1,0]
	v_cndmask_b32_e32 v18, v34, v18, vcc
	v_pk_mul_f32 v[92:93], v[16:17], v[20:21]
	v_rsq_f32_e32 v20, v18
	v_pk_mul_f32 v[16:17], v[36:37], v[24:25] op_sel_hi:[1,0]
	v_pk_mul_f32 v[18:19], v[38:39], v[24:25] op_sel_hi:[1,0]
	v_pk_mul_f32 v[96:97], v[4:5], v[16:17]
	v_mul_f32_e32 v4, 0x45800000, v20
	v_cndmask_b32_e32 v4, v20, v4, vcc
	v_pk_mul_f32 v[98:99], v[6:7], v[18:19]
	v_pk_mul_f32 v[6:7], v[36:37], v[4:5] op_sel_hi:[1,0]
	v_pk_mul_f32 v[16:17], v[38:39], v[4:5] op_sel_hi:[1,0]
	v_pk_mul_f32 v[100:101], v[0:1], v[6:7]
	v_pk_mul_f32 v[102:103], v[2:3], v[16:17]
	v_pk_mul_f32 v[0:1], v[52:53], v[4:5] op_sel_hi:[1,0]
	v_pk_mul_f32 v[2:3], v[54:55], v[4:5] op_sel_hi:[1,0]
	v_pk_mul_f32 v[104:105], v[8:9], v[0:1]
	v_pk_mul_f32 v[106:107], v[10:11], v[2:3]
	v_pk_mul_f32 v[0:1], v[44:45], v[4:5] op_sel_hi:[1,0]
	v_pk_mul_f32 v[2:3], v[46:47], v[4:5] op_sel_hi:[1,0]
	v_pk_mul_f32 v[112:113], v[12:13], v[0:1]
	v_pk_mul_f32 v[114:115], v[14:15], v[2:3]
	v_pk_mul_f32 v[0:1], v[28:29], v[110:111] op_sel_hi:[1,0]
	v_pk_mul_f32 v[2:3], v[30:31], v[110:111] op_sel_hi:[1,0]
	v_readlane_b32 s14, v255, 6
	v_pk_mul_f32 v[110:111], v[108:109], v[2:3]
	v_pk_mul_f32 v[108:109], v[118:119], v[0:1]
	v_pk_mul_f32 v[0:1], v[28:29], v[40:41] op_sel_hi:[1,0]
	v_pk_mul_f32 v[2:3], v[30:31], v[40:41] op_sel_hi:[1,0]
	v_readlane_b32 s15, v255, 7
	v_pk_mul_f32 v[118:119], v[116:117], v[2:3]
	v_pk_mul_f32 v[116:117], v[122:123], v[0:1]
	v_pk_mul_f32 v[0:1], v[28:29], v[24:25] op_sel_hi:[1,0]
	v_pk_mul_f32 v[2:3], v[30:31], v[24:25] op_sel_hi:[1,0]
	s_nop 0
	v_pk_mul_f32 v[122:123], v[120:121], v[2:3]
	v_pk_mul_f32 v[120:121], v[124:125], v[0:1]
	v_pk_mul_f32 v[0:1], v[28:29], v[4:5] op_sel_hi:[1,0]
	v_pk_mul_f32 v[2:3], v[30:31], v[4:5] op_sel_hi:[1,0]
	v_pk_mul_f32 v[124:125], v[60:61], v[0:1]
	v_pk_mul_f32 v[126:127], v[62:63], v[2:3]

.LBB0_221:
	s_or_b64 exec, exec, s[4:5]
	v_and_b32_e32 v12, 3, v129
	v_or_b32_e32 v4, s6, v12
	v_lshl_add_u64 v[0:1], s[60:61], 0, v[142:143]
	v_lshlrev_b32_e32 v4, 15, v4
	v_mov_b32_e32 v5, v197
	v_lshlrev_b32_e32 v2, 8, v12
	v_mov_b32_e32 v3, v197
	v_lshl_add_u64 v[4:5], v[0:1], 0, v[4:5]
	v_mov_b32_e32 v133, v197
	v_lshl_add_u64 v[2:3], s[0:1], 0, v[2:3]
	v_lshl_add_u64 v[4:5], v[4:5], 0, v[132:133]
	v_lshlrev_b64 v[6:7], 1, v[198:199]
	v_lshl_add_u64 v[2:3], v[198:199], 2, v[2:3]
	v_lshl_add_u64 v[4:5], v[4:5], 0, v[6:7]
	v_or_b32_e32 v8, v131, v139
	v_mov_b32_e32 v9, v197
	v_cvt_pk_bf16_f32 v10, v72, v73
	v_cvt_pk_bf16_f32 v11, v74, v75
	v_lshl_add_u64 v[8:9], v[2:3], 0, v[8:9]
	flat_store_dwordx2 v[4:5], v[10:11]
	flat_store_dwordx4 v[8:9], v[72:75] nt
	v_cvt_pk_bf16_f32 v10, v68, v69
	v_cvt_pk_bf16_f32 v11, v70, v71
	flat_store_dwordx2 v[4:5], v[10:11] offset:32
	flat_store_dwordx4 v[8:9], v[68:71] offset:64 nt
	v_cvt_pk_bf16_f32 v10, v64, v65
	v_cvt_pk_bf16_f32 v11, v66, v67
	flat_store_dwordx2 v[4:5], v[10:11] offset:64
	flat_store_dwordx4 v[8:9], v[64:67] offset:128 nt
	v_cvt_pk_bf16_f32 v10, v108, v109
	v_cvt_pk_bf16_f32 v11, v110, v111
	flat_store_dwordx2 v[4:5], v[10:11] offset:96
	flat_store_dwordx4 v[8:9], v[108:111] offset:192 nt
	v_or_b32_e32 v4, s7, v12
	v_lshlrev_b32_e32 v4, 15, v4
	v_mov_b32_e32 v5, v197
	v_lshl_add_u64 v[0:1], v[0:1], 0, v[4:5]
	v_lshl_add_u64 v[4:5], v[0:1], 0, v[196:197]
	v_lshl_add_u64 v[4:5], v[4:5], 0, v[6:7]
	v_or_b32_e32 v196, v131, v144
	v_cvt_pk_bf16_f32 v10, v84, v85
	v_cvt_pk_bf16_f32 v11, v86, v87
	v_lshl_add_u64 v[8:9], v[2:3], 0, v[196:197]
	flat_store_dwordx2 v[4:5], v[10:11]
	flat_store_dwordx4 v[8:9], v[84:87] nt
	v_cvt_pk_bf16_f32 v10, v80, v81
	v_cvt_pk_bf16_f32 v11, v82, v83
	flat_store_dwordx2 v[4:5], v[10:11] offset:32
	flat_store_dwordx4 v[8:9], v[80:83] offset:64 nt
	v_cvt_pk_bf16_f32 v10, v76, v77
	v_cvt_pk_bf16_f32 v11, v78, v79
	flat_store_dwordx2 v[4:5], v[10:11] offset:64
	flat_store_dwordx4 v[8:9], v[76:79] offset:128 nt
	v_cvt_pk_bf16_f32 v10, v116, v117
	v_cvt_pk_bf16_f32 v11, v118, v119
	v_mov_b32_e32 v135, v197
	flat_store_dwordx2 v[4:5], v[10:11] offset:96
	flat_store_dwordx4 v[8:9], v[116:119] offset:192 nt
	v_lshl_add_u64 v[4:5], v[0:1], 0, v[134:135]
	v_lshl_add_u64 v[4:5], v[4:5], 0, v[6:7]
	v_or_b32_e32 v196, v131, v145
	v_cvt_pk_bf16_f32 v10, v96, v97
	v_cvt_pk_bf16_f32 v11, v98, v99
	v_lshl_add_u64 v[8:9], v[2:3], 0, v[196:197]
	flat_store_dwordx2 v[4:5], v[10:11]
	flat_store_dwordx4 v[8:9], v[96:99] nt
	v_cvt_pk_bf16_f32 v10, v92, v93
	v_cvt_pk_bf16_f32 v11, v94, v95
	flat_store_dwordx2 v[4:5], v[10:11] offset:32
	flat_store_dwordx4 v[8:9], v[92:95] offset:64 nt
	v_cvt_pk_bf16_f32 v10, v88, v89
	v_cvt_pk_bf16_f32 v11, v90, v91
	v_mov_b32_e32 v137, v197
	flat_store_dwordx2 v[4:5], v[10:11] offset:64
	flat_store_dwordx4 v[8:9], v[88:91] offset:128 nt
	v_cvt_pk_bf16_f32 v10, v120, v121
	v_cvt_pk_bf16_f32 v11, v122, v123
	v_lshl_add_u64 v[0:1], v[0:1], 0, v[136:137]
	flat_store_dwordx2 v[4:5], v[10:11] offset:96
	flat_store_dwordx4 v[8:9], v[120:123] offset:192 nt
	v_lshl_add_u64 v[0:1], v[0:1], 0, v[6:7]
	v_or_b32_e32 v196, v131, v146
	v_cvt_pk_bf16_f32 v4, v100, v101
	v_cvt_pk_bf16_f32 v5, v102, v103
	v_lshl_add_u64 v[2:3], v[2:3], 0, v[196:197]
	flat_store_dwordx2 v[0:1], v[4:5]
	flat_store_dwordx4 v[2:3], v[100:103] nt
	v_cvt_pk_bf16_f32 v4, v104, v105
	v_cvt_pk_bf16_f32 v5, v106, v107
	flat_store_dwordx2 v[0:1], v[4:5] offset:32
	flat_store_dwordx4 v[2:3], v[104:107] offset:64 nt
	v_cvt_pk_bf16_f32 v4, v112, v113
	v_cvt_pk_bf16_f32 v5, v114, v115
	flat_store_dwordx2 v[0:1], v[4:5] offset:64
	flat_store_dwordx4 v[2:3], v[112:115] offset:128 nt
	v_cvt_pk_bf16_f32 v4, v124, v125
	v_cvt_pk_bf16_f32 v5, v126, v127
	s_mov_b64 s[0:1], 0
	flat_store_dwordx2 v[0:1], v[4:5] offset:96
	flat_store_dwordx4 v[2:3], v[124:127] offset:192 nt

.LBB0_242:
	s_andn2_b64 vcc, exec, s[18:19]
	s_cbranch_vccnz .LBB0_244
	v_lshlrev_b32_e32 v196, 6, v144
	v_lshl_add_u64 v[128:129], v[196:197], 2, s[60:61]
	v_lshlrev_b32_e32 v196, 4, v222
	v_lshl_add_u64 v[128:129], v[128:129], 0, v[196:197]
	v_lshlrev_b64 v[130:131], 10, v[204:205]
	v_lshl_add_u64 v[128:129], v[128:129], 0, v[130:131]
	s_mov_b64 s[8:9], 0x7e8da00
	v_add_co_u32_e32 v132, vcc, 0x7e8d000, v128
	v_lshl_add_u64 v[130:131], v[128:129], 0, s[8:9]
	s_nop 0
	v_addc_co_u32_e32 v133, vcc, 0, v129, vcc
	s_mov_b64 s[8:9], 0x7e91a00
	flat_store_dwordx4 v[132:133], v[84:87] offset:2560 nt
	flat_store_dwordx4 v[130:131], v[76:79] offset:64 nt
	flat_store_dwordx4 v[130:131], v[72:75] offset:128 nt
	flat_store_dwordx4 v[130:131], v[88:91] offset:192 nt
	s_nop 0
	v_lshl_add_u64 v[72:73], v[128:129], 0, s[8:9]
	s_mov_b32 s8, 0x7e91000
	v_add_co_u32_e32 v74, vcc, s8, v128
	s_mov_b64 s[8:9], 0x7eada00
	s_nop 0
	v_addc_co_u32_e32 v75, vcc, 0, v129, vcc
	flat_store_dwordx4 v[74:75], v[68:71] offset:2560 nt
	flat_store_dwordx4 v[72:73], v[64:67] offset:64 nt
	flat_store_dwordx4 v[72:73], v[108:111] offset:128 nt
	flat_store_dwordx4 v[72:73], v[124:127] offset:192 nt
	v_lshl_add_u64 v[64:65], v[128:129], 0, s[8:9]
	s_mov_b32 s8, 0x7ead000
	v_add_co_u32_e32 v66, vcc, s8, v128
	s_mov_b64 s[8:9], 0x7eb1a00
	s_nop 0
	v_addc_co_u32_e32 v67, vcc, 0, v129, vcc
	flat_store_dwordx4 v[66:67], v[116:119] offset:2560 nt
	flat_store_dwordx4 v[64:65], v[112:115] offset:64 nt
	flat_store_dwordx4 v[64:65], v[104:107] offset:128 nt
	flat_store_dwordx4 v[64:65], v[120:123] offset:192 nt
	v_add_co_u32_e32 v66, vcc, 0x7eb1000, v128
	v_lshl_add_u64 v[64:65], v[128:129], 0, s[8:9]
	s_nop 0
	v_addc_co_u32_e32 v67, vcc, 0, v129, vcc
	flat_store_dwordx4 v[66:67], v[100:103] offset:2560 nt
	flat_store_dwordx4 v[64:65], v[96:99] offset:64 nt
	flat_store_dwordx4 v[64:65], v[92:95] offset:128 nt
	flat_store_dwordx4 v[64:65], v[80:83] offset:192 nt

.LBB0_253:
	s_or_b64 exec, exec, s[0:1]
	v_cndmask_b32_e64 v64, v215, v217, s[8:9]
	v_add_u32_e32 v64, v64, v243
	v_lshrrev_b32_e32 v75, 1, v64
	v_and_b32_e32 v77, -2, v64
	s_movk_i32 s0, 0x80
	v_bfe_u32 v72, v230, 8, 1
	v_lshlrev_b32_e64 v73, v77, s0
	s_mov_b64 s[18:19], -1
	s_andn2_b64 vcc, exec, s[16:17]
	v_cmp_eq_u32_e64 s[0:1], 1, v75
	v_cmp_lt_u32_e64 s[4:5], 1, v64
	v_add_u32_e32 v65, 7, v77
	v_cndmask_b32_e64 v74, 0, 2, s[8:9]
	s_cbranch_vccnz .LBB0_263
	v_mov_b32_e32 v66, 0x604da00
	v_mov_b32_e32 v67, 0x6c4da00
	v_cndmask_b32_e64 v196, v66, v67, s[8:9]
	v_mov_b32_e32 v66, 0x1150000
	v_mov_b32_e32 v67, 0x1110000
	v_cndmask_b32_e64 v66, v66, v67, s[0:1]
	v_mov_b32_e32 v67, 0x1100000
	v_cndmask_b32_e64 v66, v67, v66, s[4:5]
	v_readlane_b32 s0, v255, 34
	v_lshl_add_u64 v[68:69], s[60:61], 0, v[196:197]
	v_lshlrev_b32_e32 v196, 2, v66
	v_readlane_b32 s1, v255, 35
	v_sub_u32_e32 v78, 13, v77
	v_lshlrev_b32_e32 v80, v78, v204
	v_lshl_add_u64 v[66:67], s[0:1], 0, v[196:197]
	v_readlane_b32 s0, v255, 36
	s_ashr_i32 s0, s0, 5
	v_lshlrev_b32_e32 v196, 4, v222
	v_mad_u64_u32 v[70:71], s[4:5], s0, 6, v[64:65]
	v_ashrrev_i32_e32 v71, 31, v70
	v_and_b32_e32 v80, 0x1ffe, v80
	v_lshrrev_b32_e32 v81, v77, v235
	v_lshlrev_b64 v[70:71], 20, v[70:71]
	v_lshl_add_u64 v[66:67], v[66:67], 0, v[196:197]
	v_lshl_add_u64 v[70:71], v[68:69], 0, v[70:71]
	v_add_lshl_u32 v196, v80, v81, 7
	v_lshl_add_u64 v[68:69], v[70:71], 0, v[196:197]
	v_lshlrev_b32_e32 v196, 3, v222
	v_lshl_add_u64 v[68:69], v[68:69], 0, v[196:197]
	v_cvt_pk_bf16_f32 v80, v128, v129
	v_cvt_pk_bf16_f32 v81, v130, v131
	s_waitcnt vmcnt(0)
	flat_store_dwordx2 v[68:69], v[80:81]
	v_cvt_pk_bf16_f32 v80, v140, v141
	v_cvt_pk_bf16_f32 v81, v142, v143
	flat_store_dwordx2 v[68:69], v[80:81] offset:32
	v_cvt_pk_bf16_f32 v80, v132, v133
	v_cvt_pk_bf16_f32 v81, v134, v135
	v_sub_u32_e32 v76, 0x2000, v73
	v_or_b32_e32 v79, v74, v72
	flat_store_dwordx2 v[68:69], v[80:81] offset:64
	v_cvt_pk_bf16_f32 v80, v160, v161
	v_cvt_pk_bf16_f32 v81, v162, v163
	flat_store_dwordx2 v[68:69], v[80:81] offset:96
	v_cmp_ge_u32_e32 vcc, v235, v76
	v_lshlrev_b32_e32 v68, 8, v79
	v_readlane_b32 s1, v255, 37
	s_and_saveexec_b64 s[4:5], vcc
	s_cbranch_execz .LBB0_256
	s_ashr_i32 s1, s0, 31
	v_lshlrev_b64 v[80:81], v65, s[0:1]
	v_sub_u32_e32 v196, v235, v76
	v_lshl_add_u64 v[80:81], v[80:81], 0, v[196:197]
	v_lshlrev_b64 v[80:81], 10, v[80:81]
	v_mov_b32_e32 v69, v197
	v_lshl_add_u64 v[80:81], v[66:67], 0, v[80:81]
	v_lshl_add_u64 v[80:81], v[80:81], 0, v[68:69]
	flat_store_dwordx4 v[80:81], v[128:131] nt
	flat_store_dwordx4 v[80:81], v[140:143] offset:64 nt
	flat_store_dwordx4 v[80:81], v[132:135] offset:128 nt
	flat_store_dwordx4 v[80:81], v[160:163] offset:192 nt
.LBB0_256:
	s_or_b64 exec, exec, s[4:5]
	v_lshlrev_b32_e32 v79, v78, v202
	v_and_b32_e32 v79, 0x1ffe, v79
	v_lshrrev_b32_e32 v80, v77, v234
	v_lshlrev_b32_e32 v69, 2, v222
	v_add_lshl_u32 v196, v79, v80, 7
	v_lshl_add_u64 v[80:81], v[70:71], 0, v[196:197]
	v_lshlrev_b32_e32 v196, 1, v69
	v_lshl_add_u64 v[80:81], v[80:81], 0, v[196:197]
	v_cvt_pk_bf16_f32 v82, v136, v137
	v_cvt_pk_bf16_f32 v83, v138, v139
	flat_store_dwordx2 v[80:81], v[82:83]
	v_cvt_pk_bf16_f32 v82, v148, v149
	v_cvt_pk_bf16_f32 v83, v150, v151
	flat_store_dwordx2 v[80:81], v[82:83] offset:32
	v_cvt_pk_bf16_f32 v82, v144, v145
	v_cvt_pk_bf16_f32 v83, v146, v147
	flat_store_dwordx2 v[80:81], v[82:83] offset:64
	v_cvt_pk_bf16_f32 v82, v168, v169
	v_cvt_pk_bf16_f32 v83, v170, v171
	v_cmp_ge_u32_e32 vcc, v234, v76
	flat_store_dwordx2 v[80:81], v[82:83] offset:96
	s_and_saveexec_b64 s[4:5], vcc
	s_cbranch_execz .LBB0_258
	s_ashr_i32 s1, s0, 31
	v_lshlrev_b64 v[80:81], v65, s[0:1]
	v_sub_u32_e32 v82, v234, v76
	v_mov_b32_e32 v83, v197
	v_lshl_add_u64 v[80:81], v[80:81], 0, v[82:83]
	v_lshlrev_b64 v[80:81], 10, v[80:81]
	v_mov_b32_e32 v69, v197
	v_lshl_add_u64 v[80:81], v[66:67], 0, v[80:81]
	v_lshl_add_u64 v[80:81], v[80:81], 0, v[68:69]
	flat_store_dwordx4 v[80:81], v[136:139] nt
	flat_store_dwordx4 v[80:81], v[148:151] offset:64 nt
	flat_store_dwordx4 v[80:81], v[144:147] offset:128 nt
	flat_store_dwordx4 v[80:81], v[168:171] offset:192 nt
.LBB0_258:
	s_or_b64 exec, exec, s[4:5]
	v_lshlrev_b32_e32 v69, v78, v200
	v_and_b32_e32 v69, 0x1ffe, v69
	v_lshrrev_b32_e32 v79, v77, v233
	v_add_lshl_u32 v80, v69, v79, 7
	v_mov_b32_e32 v81, v197
	v_lshl_add_u64 v[80:81], v[70:71], 0, v[80:81]
	v_lshl_add_u64 v[80:81], v[80:81], 0, v[196:197]
	v_cvt_pk_bf16_f32 v82, v152, v153
	v_cvt_pk_bf16_f32 v83, v154, v155
	flat_store_dwordx2 v[80:81], v[82:83]
	v_cvt_pk_bf16_f32 v82, v164, v165
	v_cvt_pk_bf16_f32 v83, v166, v167
	flat_store_dwordx2 v[80:81], v[82:83] offset:32
	v_cvt_pk_bf16_f32 v82, v156, v157
	v_cvt_pk_bf16_f32 v83, v158, v159
	flat_store_dwordx2 v[80:81], v[82:83] offset:64
	v_cvt_pk_bf16_f32 v82, v180, v181
	v_cvt_pk_bf16_f32 v83, v182, v183
	v_cmp_ge_u32_e32 vcc, v233, v76
	flat_store_dwordx2 v[80:81], v[82:83] offset:96
	s_and_saveexec_b64 s[4:5], vcc
	s_cbranch_execz .LBB0_260
	s_ashr_i32 s1, s0, 31
	v_lshlrev_b64 v[80:81], v65, s[0:1]
	v_sub_u32_e32 v82, v233, v76
	v_mov_b32_e32 v83, v197
	v_lshl_add_u64 v[80:81], v[80:81], 0, v[82:83]
	v_lshlrev_b64 v[80:81], 10, v[80:81]
	v_mov_b32_e32 v69, v197
	v_lshl_add_u64 v[80:81], v[66:67], 0, v[80:81]
	v_lshl_add_u64 v[80:81], v[80:81], 0, v[68:69]
	flat_store_dwordx4 v[80:81], v[152:155] nt
	flat_store_dwordx4 v[80:81], v[164:167] offset:64 nt
	flat_store_dwordx4 v[80:81], v[156:159] offset:128 nt
	flat_store_dwordx4 v[80:81], v[180:183] offset:192 nt
.LBB0_260:
	s_or_b64 exec, exec, s[4:5]
	v_lshlrev_b32_e32 v69, v78, v198
	v_and_b32_e32 v69, 0x1ffe, v69
	v_lshrrev_b32_e32 v77, v77, v223
	v_add_lshl_u32 v78, v69, v77, 7
	v_mov_b32_e32 v79, v197
	v_lshl_add_u64 v[70:71], v[70:71], 0, v[78:79]
	v_lshl_add_u64 v[70:71], v[70:71], 0, v[196:197]
	v_cvt_pk_bf16_f32 v78, v184, v185
	v_cvt_pk_bf16_f32 v79, v186, v187
	flat_store_dwordx2 v[70:71], v[78:79]
	v_cvt_pk_bf16_f32 v78, v172, v173
	v_cvt_pk_bf16_f32 v79, v174, v175
	flat_store_dwordx2 v[70:71], v[78:79] offset:32
	v_cvt_pk_bf16_f32 v78, v176, v177
	v_cvt_pk_bf16_f32 v79, v178, v179
	flat_store_dwordx2 v[70:71], v[78:79] offset:64
	v_cvt_pk_bf16_f32 v78, v188, v189
	v_cvt_pk_bf16_f32 v79, v190, v191
	v_cmp_ge_u32_e32 vcc, v223, v76
	flat_store_dwordx2 v[70:71], v[78:79] offset:96
	s_and_saveexec_b64 s[4:5], vcc
	s_cbranch_execz .LBB0_262
	s_ashr_i32 s1, s0, 31
	v_lshlrev_b64 v[70:71], v65, s[0:1]
	v_sub_u32_e32 v196, v223, v76
	v_lshl_add_u64 v[70:71], v[70:71], 0, v[196:197]
	v_lshlrev_b64 v[70:71], 10, v[70:71]
	v_mov_b32_e32 v69, v197
	v_lshl_add_u64 v[66:67], v[66:67], 0, v[70:71]
	v_lshl_add_u64 v[66:67], v[66:67], 0, v[68:69]
	flat_store_dwordx4 v[66:67], v[184:187] nt
	flat_store_dwordx4 v[66:67], v[172:175] offset:64 nt
	flat_store_dwordx4 v[66:67], v[176:179] offset:128 nt
	flat_store_dwordx4 v[66:67], v[188:191] offset:192 nt

.LBB0_263:
	s_and_b64 vcc, exec, s[18:19]
	s_cbranch_vccz .LBB0_265
	v_cmp_eq_u32_e32 vcc, 1, v75
	v_mov_b32_e32 v66, 0x2690000
	v_readlane_b32 s0, v255, 34
	v_cndmask_b32_e32 v66, v66, v254, vcc
	v_cmp_lt_u32_e32 vcc, 1, v64
	v_mov_b32_e32 v64, 0x1290000
	v_readlane_b32 s1, v255, 35
	v_cndmask_b32_e32 v64, v64, v66, vcc
	v_lshlrev_b32_e32 v196, 2, v64
	v_lshl_add_u64 v[66:67], s[0:1], 0, v[196:197]
	v_add_u32_e32 v64, 0xffffc000, v204
	v_lshlrev_b32_e32 v68, 4, v222
	v_mov_b32_e32 v69, v197
	v_lshl_add_u64 v[66:67], v[66:67], 0, v[68:69]
	v_ashrrev_i32_e32 v68, 3, v64
	v_ashrrev_i32_e32 v69, 31, v68
	v_add3_u32 v196, v73, v237, -8
	v_lshlrev_b64 v[68:69], v65, v[68:69]
	v_lshl_add_u64 v[68:69], v[68:69], 0, v[196:197]
	v_or_b32_e32 v70, v74, v72
	v_lshlrev_b64 v[68:69], 10, v[68:69]
	v_lshlrev_b32_e32 v70, 8, v70
	v_mov_b32_e32 v71, v197
	v_lshl_add_u64 v[68:69], v[66:67], 0, v[68:69]
	v_lshl_add_u64 v[68:69], v[68:69], 0, v[70:71]
	v_add_u32_e32 v64, 0xffffc010, v204
	s_waitcnt vmcnt(0)
	flat_store_dwordx4 v[68:69], v[128:131] nt
	flat_store_dwordx4 v[68:69], v[140:143] offset:64 nt
	flat_store_dwordx4 v[68:69], v[132:135] offset:128 nt
	flat_store_dwordx4 v[68:69], v[160:163] offset:192 nt
	v_ashrrev_i32_e32 v68, 3, v64
	v_ashrrev_i32_e32 v69, 31, v68
	v_lshlrev_b64 v[68:69], v65, v[68:69]
	v_lshl_add_u64 v[68:69], v[68:69], 0, v[196:197]
	v_lshlrev_b64 v[68:69], 10, v[68:69]
	v_lshl_add_u64 v[68:69], v[66:67], 0, v[68:69]
	v_lshl_add_u64 v[68:69], v[68:69], 0, v[70:71]
	v_add_u32_e32 v64, 0xffffc080, v204
	flat_store_dwordx4 v[68:69], v[136:139] nt
	flat_store_dwordx4 v[68:69], v[148:151] offset:64 nt
	flat_store_dwordx4 v[68:69], v[144:147] offset:128 nt
	flat_store_dwordx4 v[68:69], v[168:171] offset:192 nt
	v_ashrrev_i32_e32 v68, 3, v64
	v_ashrrev_i32_e32 v69, 31, v68
	v_lshlrev_b64 v[68:69], v65, v[68:69]
	v_lshl_add_u64 v[68:69], v[68:69], 0, v[196:197]
	v_lshlrev_b64 v[68:69], 10, v[68:69]
	v_lshl_add_u64 v[68:69], v[66:67], 0, v[68:69]
	v_lshl_add_u64 v[68:69], v[68:69], 0, v[70:71]
	v_add_u32_e32 v64, 0xffffc090, v204
	flat_store_dwordx4 v[68:69], v[152:155] nt
	flat_store_dwordx4 v[68:69], v[164:167] offset:64 nt
	flat_store_dwordx4 v[68:69], v[156:159] offset:128 nt
	flat_store_dwordx4 v[68:69], v[180:183] offset:192 nt
	v_ashrrev_i32_e32 v68, 3, v64
	v_ashrrev_i32_e32 v69, 31, v68
	v_lshlrev_b64 v[64:65], v65, v[68:69]
	v_lshl_add_u64 v[64:65], v[64:65], 0, v[196:197]
	v_lshlrev_b64 v[64:65], 10, v[64:65]
	v_lshl_add_u64 v[64:65], v[66:67], 0, v[64:65]
	v_lshl_add_u64 v[64:65], v[64:65], 0, v[70:71]
	flat_store_dwordx4 v[64:65], v[184:187] nt
	flat_store_dwordx4 v[64:65], v[172:175] offset:64 nt
	flat_store_dwordx4 v[64:65], v[176:179] offset:128 nt
	flat_store_dwordx4 v[64:65], v[188:191] offset:192 nt

.LBB0_269:
	s_andn2_b64 vcc, exec, s[0:1]
	s_cbranch_vccnz .LBB0_271
	v_lshlrev_b32_e32 v196, 6, v160
	v_lshl_add_u64 v[72:73], v[196:197], 2, s[60:61]
	v_lshlrev_b32_e32 v196, 4, v222
	v_lshl_add_u64 v[72:73], v[72:73], 0, v[196:197]
	s_mov_b64 s[0:1], 0x784da00
	v_add_u32_e32 v74, 0xffffc000, v204
	v_lshl_add_u64 v[72:73], v[72:73], 0, s[0:1]
	s_movk_i32 s4, 0x600
	v_mad_i64_i32 v[74:75], s[0:1], v74, s4, v[72:73]
	flat_store_dwordx4 v[74:75], v[68:71] nt
	flat_store_dwordx4 v[74:75], v[84:87] offset:64 nt
	flat_store_dwordx4 v[74:75], v[76:79] offset:128 nt
	flat_store_dwordx4 v[74:75], v[88:91] offset:192 nt
	v_add_u32_e32 v68, 0xffffc010, v204
	v_mad_i64_i32 v[68:69], s[0:1], v68, s4, v[72:73]
	flat_store_dwordx4 v[68:69], v[92:95] nt
	flat_store_dwordx4 v[68:69], v[64:67] offset:64 nt
	flat_store_dwordx4 v[68:69], v[80:83] offset:128 nt
	flat_store_dwordx4 v[68:69], v[96:99] offset:192 nt
	v_add_u32_e32 v64, 0xffffc080, v204
	v_mad_i64_i32 v[64:65], s[0:1], v64, s4, v[72:73]
	flat_store_dwordx4 v[64:65], v[100:103] nt
	flat_store_dwordx4 v[64:65], v[108:111] offset:64 nt
	flat_store_dwordx4 v[64:65], v[104:107] offset:128 nt
	flat_store_dwordx4 v[64:65], v[120:123] offset:192 nt
	v_add_u32_e32 v64, 0xffffc090, v204
	v_mad_i64_i32 v[64:65], s[0:1], v64, s4, v[72:73]
	flat_store_dwordx4 v[64:65], v[128:131] nt
	flat_store_dwordx4 v[64:65], v[116:119] offset:64 nt
	flat_store_dwordx4 v[64:65], v[112:115] offset:128 nt
	flat_store_dwordx4 v[64:65], v[124:127] offset:192 nt

.LBB0_301:
	s_andn2_b64 vcc, exec, s[18:19]
	s_cbranch_vccnz .LBB0_303
	v_lshlrev_b32_e32 v196, 6, v80
	v_lshl_add_u64 v[64:65], v[196:197], 2, s[60:61]
	v_lshlrev_b32_e32 v196, 4, v222
	v_lshl_add_u64 v[64:65], v[64:65], 0, v[196:197]
	v_lshlrev_b64 v[66:67], 10, v[204:205]
	v_lshl_add_u64 v[64:65], v[64:65], 0, v[66:67]
	s_mov_b64 s[8:9], 0x7e8da00
	v_add_co_u32_e32 v68, vcc, 0x7e8d000, v64
	v_lshl_add_u64 v[66:67], v[64:65], 0, s[8:9]
	s_nop 0
	v_addc_co_u32_e32 v69, vcc, 0, v65, vcc
	s_mov_b64 s[8:9], 0x7e91a00
	flat_store_dwordx4 v[68:69], v[20:23] offset:2560 nt
	flat_store_dwordx4 v[66:67], v[12:15] offset:64 nt
	flat_store_dwordx4 v[66:67], v[8:11] offset:128 nt
	flat_store_dwordx4 v[66:67], v[24:27] offset:192 nt
	s_nop 0
	v_lshl_add_u64 v[8:9], v[64:65], 0, s[8:9]
	s_mov_b32 s8, 0x7e91000
	v_add_co_u32_e32 v10, vcc, s8, v64
	s_mov_b64 s[8:9], 0x7eada00
	s_nop 0
	v_addc_co_u32_e32 v11, vcc, 0, v65, vcc
	flat_store_dwordx4 v[10:11], v[4:7] offset:2560 nt
	flat_store_dwordx4 v[8:9], v[0:3] offset:64 nt
	flat_store_dwordx4 v[8:9], v[44:47] offset:128 nt
	flat_store_dwordx4 v[8:9], v[60:63] offset:192 nt
	v_lshl_add_u64 v[0:1], v[64:65], 0, s[8:9]
	s_mov_b32 s8, 0x7ead000
	v_add_co_u32_e32 v2, vcc, s8, v64
	s_mov_b64 s[8:9], 0x7eb1a00
	s_nop 0
	v_addc_co_u32_e32 v3, vcc, 0, v65, vcc
	flat_store_dwordx4 v[2:3], v[52:55] offset:2560 nt
	flat_store_dwordx4 v[0:1], v[48:51] offset:64 nt
	flat_store_dwordx4 v[0:1], v[40:43] offset:128 nt
	flat_store_dwordx4 v[0:1], v[56:59] offset:192 nt
	v_add_co_u32_e32 v2, vcc, 0x7eb1000, v64
	v_lshl_add_u64 v[0:1], v[64:65], 0, s[8:9]
	s_nop 0
	v_addc_co_u32_e32 v3, vcc, 0, v65, vcc
	flat_store_dwordx4 v[2:3], v[36:39] offset:2560 nt
	flat_store_dwordx4 v[0:1], v[32:35] offset:64 nt
	flat_store_dwordx4 v[0:1], v[28:31] offset:128 nt
	flat_store_dwordx4 v[0:1], v[16:19] offset:192 nt

.LBB0_312:
	s_or_b64 exec, exec, s[0:1]
	v_cndmask_b32_e64 v0, v215, v217, s[8:9]
	v_add_u32_e32 v0, v0, v129
	v_lshrrev_b32_e32 v11, 1, v0
	v_and_b32_e32 v13, -2, v0
	s_movk_i32 s0, 0x80
	v_bfe_u32 v8, v230, 8, 1
	v_lshlrev_b32_e64 v9, v13, s0
	s_mov_b64 s[18:19], -1
	s_andn2_b64 vcc, exec, s[16:17]
	v_cmp_eq_u32_e64 s[0:1], 1, v11
	v_cmp_lt_u32_e64 s[4:5], 1, v0
	v_add_u32_e32 v1, 7, v13
	v_cndmask_b32_e64 v10, 0, 2, s[8:9]
	s_cbranch_vccnz .LBB0_322
	v_mov_b32_e32 v2, 0x604da00
	v_mov_b32_e32 v3, 0x6c4da00
	v_cndmask_b32_e64 v196, v2, v3, s[8:9]
	v_mov_b32_e32 v2, 0x1150000
	v_mov_b32_e32 v3, 0x1110000
	v_cndmask_b32_e64 v2, v2, v3, s[0:1]
	v_mov_b32_e32 v3, 0x1100000
	v_cndmask_b32_e64 v2, v3, v2, s[4:5]
	v_readlane_b32 s0, v255, 34
	v_lshl_add_u64 v[4:5], s[60:61], 0, v[196:197]
	v_lshlrev_b32_e32 v196, 2, v2
	v_readlane_b32 s1, v255, 35
	v_sub_u32_e32 v14, 13, v13
	v_lshlrev_b32_e32 v16, v14, v204
	v_lshl_add_u64 v[2:3], s[0:1], 0, v[196:197]
	v_readlane_b32 s0, v255, 36
	s_ashr_i32 s0, s0, 5
	v_lshlrev_b32_e32 v196, 4, v222
	v_mad_u64_u32 v[6:7], s[4:5], s0, 6, v[0:1]
	v_ashrrev_i32_e32 v7, 31, v6
	v_and_b32_e32 v16, 0x1ffe, v16
	v_lshrrev_b32_e32 v17, v13, v235
	v_lshlrev_b64 v[6:7], 20, v[6:7]
	v_lshl_add_u64 v[2:3], v[2:3], 0, v[196:197]
	v_lshl_add_u64 v[6:7], v[4:5], 0, v[6:7]
	v_add_lshl_u32 v196, v16, v17, 7
	v_lshl_add_u64 v[4:5], v[6:7], 0, v[196:197]
	v_lshlrev_b32_e32 v196, 3, v222
	v_lshl_add_u64 v[4:5], v[4:5], 0, v[196:197]
	v_cvt_pk_bf16_f32 v16, v64, v65
	s_waitcnt lgkmcnt(0)
	v_cvt_pk_bf16_f32 v17, v66, v67
	s_waitcnt vmcnt(0)
	flat_store_dwordx2 v[4:5], v[16:17]
	v_cvt_pk_bf16_f32 v16, v76, v77
	v_cvt_pk_bf16_f32 v17, v78, v79
	flat_store_dwordx2 v[4:5], v[16:17] offset:32
	v_cvt_pk_bf16_f32 v16, v68, v69
	v_cvt_pk_bf16_f32 v17, v70, v71
	v_sub_u32_e32 v12, 0x2000, v9
	v_or_b32_e32 v15, v10, v8
	flat_store_dwordx2 v[4:5], v[16:17] offset:64
	v_cvt_pk_bf16_f32 v16, v96, v97
	v_cvt_pk_bf16_f32 v17, v98, v99
	flat_store_dwordx2 v[4:5], v[16:17] offset:96
	v_cmp_ge_u32_e32 vcc, v235, v12
	v_lshlrev_b32_e32 v4, 8, v15
	v_readlane_b32 s1, v255, 37
	s_and_saveexec_b64 s[4:5], vcc
	s_cbranch_execz .LBB0_315
	s_ashr_i32 s1, s0, 31
	v_lshlrev_b64 v[16:17], v1, s[0:1]
	v_sub_u32_e32 v196, v235, v12
	v_lshl_add_u64 v[16:17], v[16:17], 0, v[196:197]
	v_lshlrev_b64 v[16:17], 10, v[16:17]
	v_mov_b32_e32 v5, v197
	v_lshl_add_u64 v[16:17], v[2:3], 0, v[16:17]
	v_lshl_add_u64 v[16:17], v[16:17], 0, v[4:5]
	flat_store_dwordx4 v[16:17], v[64:67] nt
	flat_store_dwordx4 v[16:17], v[76:79] offset:64 nt
	flat_store_dwordx4 v[16:17], v[68:71] offset:128 nt
	flat_store_dwordx4 v[16:17], v[96:99] offset:192 nt
.LBB0_315:
	s_or_b64 exec, exec, s[4:5]
	v_lshlrev_b32_e32 v15, v14, v202
	v_and_b32_e32 v15, 0x1ffe, v15
	v_lshrrev_b32_e32 v16, v13, v234
	v_lshlrev_b32_e32 v5, 2, v222
	v_add_lshl_u32 v196, v15, v16, 7
	v_lshl_add_u64 v[16:17], v[6:7], 0, v[196:197]
	v_lshlrev_b32_e32 v196, 1, v5
	v_lshl_add_u64 v[16:17], v[16:17], 0, v[196:197]
	v_cvt_pk_bf16_f32 v18, v72, v73
	v_cvt_pk_bf16_f32 v19, v74, v75
	flat_store_dwordx2 v[16:17], v[18:19]
	v_cvt_pk_bf16_f32 v18, v84, v85
	v_cvt_pk_bf16_f32 v19, v86, v87
	flat_store_dwordx2 v[16:17], v[18:19] offset:32
	v_cvt_pk_bf16_f32 v18, v80, v81
	v_cvt_pk_bf16_f32 v19, v82, v83
	flat_store_dwordx2 v[16:17], v[18:19] offset:64
	v_cvt_pk_bf16_f32 v18, v104, v105
	v_cvt_pk_bf16_f32 v19, v106, v107
	v_cmp_ge_u32_e32 vcc, v234, v12
	flat_store_dwordx2 v[16:17], v[18:19] offset:96
	s_and_saveexec_b64 s[4:5], vcc
	s_cbranch_execz .LBB0_317
	s_ashr_i32 s1, s0, 31
	v_lshlrev_b64 v[16:17], v1, s[0:1]
	v_sub_u32_e32 v18, v234, v12
	v_mov_b32_e32 v19, v197
	v_lshl_add_u64 v[16:17], v[16:17], 0, v[18:19]
	v_lshlrev_b64 v[16:17], 10, v[16:17]
	v_mov_b32_e32 v5, v197
	v_lshl_add_u64 v[16:17], v[2:3], 0, v[16:17]
	v_lshl_add_u64 v[16:17], v[16:17], 0, v[4:5]
	flat_store_dwordx4 v[16:17], v[72:75] nt
	flat_store_dwordx4 v[16:17], v[84:87] offset:64 nt
	flat_store_dwordx4 v[16:17], v[80:83] offset:128 nt
	flat_store_dwordx4 v[16:17], v[104:107] offset:192 nt
.LBB0_317:
	s_or_b64 exec, exec, s[4:5]
	v_lshlrev_b32_e32 v5, v14, v200
	v_and_b32_e32 v5, 0x1ffe, v5
	v_lshrrev_b32_e32 v15, v13, v233
	v_add_lshl_u32 v16, v5, v15, 7
	v_mov_b32_e32 v17, v197
	v_lshl_add_u64 v[16:17], v[6:7], 0, v[16:17]
	v_lshl_add_u64 v[16:17], v[16:17], 0, v[196:197]
	v_cvt_pk_bf16_f32 v18, v88, v89
	v_cvt_pk_bf16_f32 v19, v90, v91
	flat_store_dwordx2 v[16:17], v[18:19]
	v_cvt_pk_bf16_f32 v18, v100, v101
	v_cvt_pk_bf16_f32 v19, v102, v103
	flat_store_dwordx2 v[16:17], v[18:19] offset:32
	v_cvt_pk_bf16_f32 v18, v92, v93
	v_cvt_pk_bf16_f32 v19, v94, v95
	flat_store_dwordx2 v[16:17], v[18:19] offset:64
	v_cvt_pk_bf16_f32 v18, v116, v117
	v_cvt_pk_bf16_f32 v19, v118, v119
	v_cmp_ge_u32_e32 vcc, v233, v12
	flat_store_dwordx2 v[16:17], v[18:19] offset:96
	s_and_saveexec_b64 s[4:5], vcc
	s_cbranch_execz .LBB0_319
	s_ashr_i32 s1, s0, 31
	v_lshlrev_b64 v[16:17], v1, s[0:1]
	v_sub_u32_e32 v18, v233, v12
	v_mov_b32_e32 v19, v197
	v_lshl_add_u64 v[16:17], v[16:17], 0, v[18:19]
	v_lshlrev_b64 v[16:17], 10, v[16:17]
	v_mov_b32_e32 v5, v197
	v_lshl_add_u64 v[16:17], v[2:3], 0, v[16:17]
	v_lshl_add_u64 v[16:17], v[16:17], 0, v[4:5]
	flat_store_dwordx4 v[16:17], v[88:91] nt
	flat_store_dwordx4 v[16:17], v[100:103] offset:64 nt
	flat_store_dwordx4 v[16:17], v[92:95] offset:128 nt
	flat_store_dwordx4 v[16:17], v[116:119] offset:192 nt
.LBB0_319:
	s_or_b64 exec, exec, s[4:5]
	v_lshlrev_b32_e32 v5, v14, v198
	v_and_b32_e32 v5, 0x1ffe, v5
	v_lshrrev_b32_e32 v13, v13, v223
	v_add_lshl_u32 v14, v5, v13, 7
	v_mov_b32_e32 v15, v197
	v_lshl_add_u64 v[6:7], v[6:7], 0, v[14:15]
	v_lshl_add_u64 v[6:7], v[6:7], 0, v[196:197]
	v_cvt_pk_bf16_f32 v14, v120, v121
	v_cvt_pk_bf16_f32 v15, v122, v123
	flat_store_dwordx2 v[6:7], v[14:15]
	v_cvt_pk_bf16_f32 v14, v108, v109
	v_cvt_pk_bf16_f32 v15, v110, v111
	flat_store_dwordx2 v[6:7], v[14:15] offset:32
	v_cvt_pk_bf16_f32 v14, v112, v113
	v_cvt_pk_bf16_f32 v15, v114, v115
	flat_store_dwordx2 v[6:7], v[14:15] offset:64
	v_cvt_pk_bf16_f32 v14, v124, v125
	v_cvt_pk_bf16_f32 v15, v126, v127
	v_cmp_ge_u32_e32 vcc, v223, v12
	flat_store_dwordx2 v[6:7], v[14:15] offset:96
	s_and_saveexec_b64 s[4:5], vcc
	s_cbranch_execz .LBB0_321
	s_ashr_i32 s1, s0, 31
	v_lshlrev_b64 v[6:7], v1, s[0:1]
	v_sub_u32_e32 v196, v223, v12
	v_lshl_add_u64 v[6:7], v[6:7], 0, v[196:197]
	v_lshlrev_b64 v[6:7], 10, v[6:7]
	v_mov_b32_e32 v5, v197
	v_lshl_add_u64 v[2:3], v[2:3], 0, v[6:7]
	v_lshl_add_u64 v[2:3], v[2:3], 0, v[4:5]
	flat_store_dwordx4 v[2:3], v[120:123] nt
	flat_store_dwordx4 v[2:3], v[108:111] offset:64 nt
	flat_store_dwordx4 v[2:3], v[112:115] offset:128 nt
	flat_store_dwordx4 v[2:3], v[124:127] offset:192 nt

.LBB0_322:
	s_and_b64 vcc, exec, s[18:19]
	s_cbranch_vccz .LBB0_324
	v_cmp_eq_u32_e32 vcc, 1, v11
	v_mov_b32_e32 v2, 0x2690000
	v_readlane_b32 s0, v255, 34
	v_cndmask_b32_e32 v2, v2, v254, vcc
	v_cmp_lt_u32_e32 vcc, 1, v0
	v_mov_b32_e32 v0, 0x1290000
	v_readlane_b32 s1, v255, 35
	v_cndmask_b32_e32 v0, v0, v2, vcc
	v_lshlrev_b32_e32 v196, 2, v0
	v_lshl_add_u64 v[2:3], s[0:1], 0, v[196:197]
	v_add_u32_e32 v0, 0xffffc000, v204
	v_lshlrev_b32_e32 v4, 4, v222
	v_mov_b32_e32 v5, v197
	v_lshl_add_u64 v[2:3], v[2:3], 0, v[4:5]
	v_ashrrev_i32_e32 v4, 3, v0
	v_ashrrev_i32_e32 v5, 31, v4
	v_add3_u32 v196, v9, v237, -8
	v_lshlrev_b64 v[4:5], v1, v[4:5]
	v_lshl_add_u64 v[4:5], v[4:5], 0, v[196:197]
	v_or_b32_e32 v6, v10, v8
	v_lshlrev_b64 v[4:5], 10, v[4:5]
	v_lshlrev_b32_e32 v6, 8, v6
	v_mov_b32_e32 v7, v197
	v_lshl_add_u64 v[4:5], v[2:3], 0, v[4:5]
	v_lshl_add_u64 v[4:5], v[4:5], 0, v[6:7]
	v_add_u32_e32 v0, 0xffffc010, v204
	s_waitcnt vmcnt(0) lgkmcnt(0)
	flat_store_dwordx4 v[4:5], v[64:67] nt
	flat_store_dwordx4 v[4:5], v[76:79] offset:64 nt
	flat_store_dwordx4 v[4:5], v[68:71] offset:128 nt
	flat_store_dwordx4 v[4:5], v[96:99] offset:192 nt
	v_ashrrev_i32_e32 v4, 3, v0
	v_ashrrev_i32_e32 v5, 31, v4
	v_lshlrev_b64 v[4:5], v1, v[4:5]
	v_lshl_add_u64 v[4:5], v[4:5], 0, v[196:197]
	v_lshlrev_b64 v[4:5], 10, v[4:5]
	v_lshl_add_u64 v[4:5], v[2:3], 0, v[4:5]
	v_lshl_add_u64 v[4:5], v[4:5], 0, v[6:7]
	v_add_u32_e32 v0, 0xffffc080, v204
	flat_store_dwordx4 v[4:5], v[72:75] nt
	flat_store_dwordx4 v[4:5], v[84:87] offset:64 nt
	flat_store_dwordx4 v[4:5], v[80:83] offset:128 nt
	flat_store_dwordx4 v[4:5], v[104:107] offset:192 nt
	v_ashrrev_i32_e32 v4, 3, v0
	v_ashrrev_i32_e32 v5, 31, v4
	v_lshlrev_b64 v[4:5], v1, v[4:5]
	v_lshl_add_u64 v[4:5], v[4:5], 0, v[196:197]
	v_lshlrev_b64 v[4:5], 10, v[4:5]
	v_lshl_add_u64 v[4:5], v[2:3], 0, v[4:5]
	v_lshl_add_u64 v[4:5], v[4:5], 0, v[6:7]
	v_add_u32_e32 v0, 0xffffc090, v204
	flat_store_dwordx4 v[4:5], v[88:91] nt
	flat_store_dwordx4 v[4:5], v[100:103] offset:64 nt
	flat_store_dwordx4 v[4:5], v[92:95] offset:128 nt
	flat_store_dwordx4 v[4:5], v[116:119] offset:192 nt
	v_ashrrev_i32_e32 v4, 3, v0
	v_ashrrev_i32_e32 v5, 31, v4
	v_lshlrev_b64 v[0:1], v1, v[4:5]
	v_lshl_add_u64 v[0:1], v[0:1], 0, v[196:197]
	v_lshlrev_b64 v[0:1], 10, v[0:1]
	v_lshl_add_u64 v[0:1], v[2:3], 0, v[0:1]
	v_lshl_add_u64 v[0:1], v[0:1], 0, v[6:7]
	flat_store_dwordx4 v[0:1], v[120:123] nt
	flat_store_dwordx4 v[0:1], v[108:111] offset:64 nt
	flat_store_dwordx4 v[0:1], v[112:115] offset:128 nt
	flat_store_dwordx4 v[0:1], v[124:127] offset:192 nt

.LBB0_328:
	s_andn2_b64 vcc, exec, s[0:1]
	s_cbranch_vccnz .LBB0_330
	v_lshlrev_b32_e32 v196, 6, v96
	v_lshl_add_u64 v[8:9], v[196:197], 2, s[60:61]
	v_lshlrev_b32_e32 v196, 4, v222
	v_lshl_add_u64 v[8:9], v[8:9], 0, v[196:197]
	s_mov_b64 s[0:1], 0x784da00
	v_add_u32_e32 v10, 0xffffc000, v204
	v_lshl_add_u64 v[8:9], v[8:9], 0, s[0:1]
	s_movk_i32 s4, 0x600
	v_mad_i64_i32 v[10:11], s[0:1], v10, s4, v[8:9]
	flat_store_dwordx4 v[10:11], v[4:7] nt
	flat_store_dwordx4 v[10:11], v[20:23] offset:64 nt
	flat_store_dwordx4 v[10:11], v[12:15] offset:128 nt
	flat_store_dwordx4 v[10:11], v[24:27] offset:192 nt
	v_add_u32_e32 v4, 0xffffc010, v204
	v_mad_i64_i32 v[4:5], s[0:1], v4, s4, v[8:9]
	flat_store_dwordx4 v[4:5], v[28:31] nt
	flat_store_dwordx4 v[4:5], v[0:3] offset:64 nt
	flat_store_dwordx4 v[4:5], v[16:19] offset:128 nt
	flat_store_dwordx4 v[4:5], v[32:35] offset:192 nt
	v_add_u32_e32 v0, 0xffffc080, v204
	v_mad_i64_i32 v[0:1], s[0:1], v0, s4, v[8:9]
	flat_store_dwordx4 v[0:1], v[36:39] nt
	flat_store_dwordx4 v[0:1], v[44:47] offset:64 nt
	flat_store_dwordx4 v[0:1], v[40:43] offset:128 nt
	flat_store_dwordx4 v[0:1], v[56:59] offset:192 nt
	v_add_u32_e32 v0, 0xffffc090, v204
	v_mad_i64_i32 v[0:1], s[0:1], v0, s4, v[8:9]
	flat_store_dwordx4 v[0:1], v[64:67] nt
	flat_store_dwordx4 v[0:1], v[52:55] offset:64 nt
	flat_store_dwordx4 v[0:1], v[48:51] offset:128 nt
	flat_store_dwordx4 v[0:1], v[60:63] offset:192 nt
